# attention unit prologue: gain wait + max-shuffle chain moved after the first chunk's DMA issue
# speedup vs baseline: 1.0081x; 1.0081x over previous
; __device__ __forceinline__ bool attn_unit(const Ptrs& P, LAS unsigned char* lds, int unit, int tid, int wave, int lane, bool pre, int nxt) {
;     ...
;     const int g = wave & 3, q0 = 64 * (wave >> 2), h = kh * 4 + g, r = lane & 31, hh = lane >> 5;
;     unsigned char* ws = P.ws;
;     bf16_t* Qb = (bf16_t*)(ws + WS_Q) + (size_t)(b * SEQ + n * 128 + q0) * DM + h * 64;
;     const bf16_t* Kg = (const bf16_t*)(ws + WS_K) + (size_t)b * SEQ * KVW + kh * 64; const bf16_t* Vg = (const bf16_t*)(ws + WS_VT) + (size_t)(b * 4 + kh) * 64 * SEQ;
;     const bf16_t* Kcg = (const bf16_t*)(ws + WS_KC) + (size_t)b * CTX * KVW + kh * 64; const bf16_t* Vcg = (const bf16_t*)(ws + WS_VCT) + (size_t)(b * 4 + kh) * 64 * CTX;
;     float mq = fabsf(P.qg[lane]), mk = fabsf(P.kg[lane]);
; #pragma unroll
;     for (int o = 1; o < 64; o <<= 1) { mq = fmaxf(mq, __shfl_xor(mq, o)); mk = fmaxf(mk, __shfl_xor(mk, o)); }
;     const float sink2 = P.sink[h] * LOG2E; const float mshift = fmaxf(64.0f * QSCALE * mq * mk, sink2);
;     bf16x8_t qf[2][4];
; #pragma unroll
;     for (int cb = 0; cb < 2; ++cb)
; #pragma unroll
;         for (int ds = 0; ds < 4; ++ds) qf[cb][ds] = __builtin_nontemporal_load((const bf16x8_t*)(Qb + (size_t)(32 * cb + r) * DM + 16 * ds + 8 * hh));
.LBB9_308:
	global_load_dword v0, v[172:173], off
	global_load_dword v2, v[174:175], off
	s_and_b32 s43, s42, 31
	s_ashr_i32 s82, s42, 7
	s_lshl_b32 s47, s43, 7
	s_lshl_b32 s46, s82, 12
	s_add_i32 s70, s47, s33
	s_add_i32 s50, s70, s46
	s_bfe_u32 s44, s42, 0x20005
	s_mov_b32 s46, s50
	s_lshl_b32 s45, s44, 2
	s_ashr_i32 s83, s82, 31
	v_readlane_b32 s48, v251, 40
	s_ashr_i32 s51, s50, 31
	v_writelane_b32 v250, s46, 17
	s_or_b32 s45, s45, s48
	s_lshl_b64 s[48:49], s[82:83], 21
	v_writelane_b32 v250, s47, 18
	s_lshl_b64 s[78:79], s[50:51], 11
	v_readlane_b32 s46, v251, 59
	s_add_u32 s46, s46, s48
	v_readlane_b32 s48, v251, 60
	s_addc_u32 s48, s48, s49
	s_lshl_b32 s49, s44, 7
	s_add_u32 s96, s46, s49
	s_addc_u32 s97, s48, 0
	s_lshl_b32 s46, s82, 2
	s_or_b32 s70, s46, s44
	s_ashr_i32 s71, s70, 31
	s_lshl_b64 s[74:75], s[70:71], 19
	v_readlane_b32 s46, v251, 63
	s_add_u32 s46, s46, s78
	v_readlane_b32 s48, v250, 0
	s_addc_u32 s49, s48, s79
	s_lshl_b32 s48, s45, 7
	s_add_u32 s48, s46, s48
	s_addc_u32 s49, s49, 0
	s_mov_b64 s[88:89], s[72:73]
	s_mov_b64 s[80:81], s[34:35]
	s_mov_b64 s[34:35], s[30:31]
	s_mov_b64 s[30:31], s[28:29]
	s_mov_b64 s[28:29], s[26:27]
	s_mov_b64 s[26:27], s[24:25]
	s_mov_b64 s[24:25], s[22:23]
	s_mov_b64 s[22:23], s[20:21]
	s_mov_b64 s[20:21], s[18:19]
	s_mov_b64 s[18:19], s[16:17]
	s_mov_b64 s[16:17], s[14:15]
	s_mov_b64 s[14:15], s[12:13]
	s_mov_b64 s[12:13], s[10:11]
	s_mov_b64 s[10:11], s[8:9]
	s_mov_b64 s[8:9], s[6:7]
	s_mov_b64 s[6:7], s[4:5]
	s_mov_b64 s[4:5], s[0:1]
	s_mov_b64 s[0:1], s[66:67]
	s_mov_b64 s[40:41], s[64:65]
	s_mov_b64 s[66:67], s[62:63]
	s_mov_b64 s[64:65], s[60:61]
	s_mov_b64 s[72:73], s[56:57]
	s_lshl_b32 s46, s45, 2
	v_lshl_add_u64 v[4:5], s[48:49], 0, v[178:179]
	s_mov_b64 s[78:79], s[54:55]
	v_readlane_b32 s48, v251, 16
	v_mov_b32_e32 v3, s46
	v_readlane_b32 s56, v251, 24
	v_readlane_b32 s57, v251, 25
	v_lshl_add_u64 v[4:5], v[4:5], 0, v[180:181]
	v_readlane_b32 s51, v251, 19
	v_readlane_b32 s46, v250, 1
	v_readlane_b32 s50, v251, 18
	v_readlane_b32 s54, v251, 22
	global_load_dword v3, v3, s[56:57]
	s_nop 0
	global_load_dwordx4 v[114:117], v[4:5], off nt
	global_load_dwordx4 v[118:121], v[4:5], off offset:32 nt
	global_load_dwordx4 v[122:125], v[4:5], off offset:64 nt
	global_load_dwordx4 v[126:129], v[4:5], off offset:96 nt
	v_add_co_u32_e32 v4, vcc, 0x10000, v4
	v_readlane_b32 s55, v251, 23
	s_nop 0
	v_addc_co_u32_e32 v5, vcc, 0, v5, vcc
	global_load_dwordx4 v[130:133], v[4:5], off nt
	global_load_dwordx4 v[134:137], v[4:5], off offset:32 nt
	global_load_dwordx4 v[138:141], v[4:5], off offset:64 nt
	global_load_dwordx4 v[142:145], v[4:5], off offset:96 nt
	s_add_u32 s51, s46, s74
	v_readlane_b32 s46, v250, 2
	s_mov_b64 s[54:55], s[78:79]
	v_readlane_b32 s50, v251, 32
	s_addc_u32 s46, s46, s75
	s_and_b64 vcc, exec, s[68:69]
	v_readlane_b32 s49, v251, 17
	v_readlane_b32 s52, v251, 20
	v_readlane_b32 s53, v251, 21
	v_readlane_b32 s58, v251, 26
	v_readlane_b32 s59, v251, 27
	v_readlane_b32 s60, v251, 28
	v_readlane_b32 s61, v251, 29
	v_readlane_b32 s62, v251, 30
	v_readlane_b32 s63, v251, 31
	s_cbranch_vccnz .LBB9_329
	s_cmp_lg_u32 s43, 0
	s_cbranch_scc0 .LBB9_319
	s_andn2_b64 vcc, exec, s[54:55]
	s_cbranch_vccnz .LBB9_318
	s_add_i32 s76, s43, -1
	s_lshl_b64 s[48:49], s[76:77], 16
	s_add_u32 s68, s96, s48
	s_addc_u32 s69, s97, s49
	s_lshl_b32 s48, s76, 8
	s_add_u32 s84, s51, s48
	s_addc_u32 s85, s46, 0
	v_mov_b32_e32 v12, v193
	s_nop 0
	s_mov_b32 s76, s50
	s_branch .LBB9_314

; __device__ __forceinline__ bool attn_unit(const Ptrs& P, LAS unsigned char* lds, int unit, int tid, int wave, int lane, bool pre, int nxt) {
;     ...
;     if (!pre) { if (n == 0) AT_DMA(1); else AT_DMA(0); }
.LBB9_319:
.LBB9_320:
	s_andn2_b64 vcc, exec, s[54:55]
	s_cbranch_vccnz .LBB9_329
	s_lshl_b32 s48, s47, 1
	s_add_u32 s68, s51, s48
	s_addc_u32 s69, s46, 0
	v_mov_b32_e32 v12, v193
	s_nop 0
	s_mov_b32 s76, s50
	s_branch .LBB9_324

; #define AT_SYNC() do { asm volatile("s_waitcnt vmcnt(0) lgkmcnt(0)" ::: "memory"); __builtin_amdgcn_s_barrier(); asm volatile("" ::: "memory"); } while (0)
; __device__ __forceinline__ bool attn_unit(const Ptrs& P, LAS unsigned char* lds, int unit, int tid, int wave, int lane, bool pre, int nxt) {
;     ...
;     float mq = fabsf(P.qg[lane]), mk = fabsf(P.kg[lane]);
; #pragma unroll
;     for (int o = 1; o < 64; o <<= 1) { mq = fmaxf(mq, __shfl_xor(mq, o)); mk = fmaxf(mk, __shfl_xor(mk, o)); }
;     const float sink2 = P.sink[h] * LOG2E; const float mshift = fmaxf(64.0f * QSCALE * mq * mk, sink2);
;     bf16x8_t qf[2][4];
; #pragma unroll
;     for (int cb = 0; cb < 2; ++cb)
; #pragma unroll
;         for (int ds = 0; ds < 4; ++ds) qf[cb][ds] = __builtin_nontemporal_load((const bf16x8_t*)(Qb + (size_t)(32 * cb + r) * DM + 16 * ds + 8 * hh));
;     f32x16 o[2][2];
; #pragma unroll
;     for (int db = 0; db < 2; ++db)
; #pragma unroll
;         for (int cb = 0; cb < 2; ++cb)
; #pragma unroll
;             for (int i = 0; i < 16; ++i) o[db][cb][i] = 0.f;
;     float rs[2] = {0.f, 0.f};
;     f32x16 negm;
; #pragma unroll
;     for (int i = 0; i < 16; ++i) negm[i] = -mshift;
;     ...
;     if (!pre) { if (n == 0) AT_DMA(1); else AT_DMA(0); }
;     AT_SYNC();
;     const int n2 = nxt & 31; const bool pf = nxt >= 0 && n2 != 0;
.LBB9_329:
	s_waitcnt vmcnt(9)
	v_and_b32_e32 v4, 0x7fffffff, v0
	v_and_b32_e32 v5, 0x7fffffff, v2
	ds_bpermute_b32 v4, v185, v4
	ds_bpermute_b32 v5, v185, v5
	v_max_f32_e64 v0, |v0|, |v0|
	v_max_f32_e64 v2, |v2|, |v2|
	s_waitcnt lgkmcnt(1)
	v_max_f32_e32 v4, v4, v4
	s_waitcnt lgkmcnt(0)
	v_max_f32_e32 v5, v5, v5
	v_max_f32_e32 v0, v0, v4
	v_max_f32_e32 v2, v2, v5
	ds_bpermute_b32 v4, v186, v0
	ds_bpermute_b32 v5, v186, v2
	s_waitcnt lgkmcnt(1)
	v_max_f32_e32 v4, v4, v4
	s_waitcnt lgkmcnt(0)
	v_max_f32_e32 v5, v5, v5
	v_max_f32_e32 v0, v0, v4
	v_max_f32_e32 v2, v2, v5
	ds_bpermute_b32 v4, v187, v0
	ds_bpermute_b32 v5, v187, v2
	s_waitcnt lgkmcnt(1)
	v_max_f32_e32 v4, v4, v4
	s_waitcnt lgkmcnt(0)
	v_max_f32_e32 v5, v5, v5
	v_max_f32_e32 v0, v0, v4
	v_max_f32_e32 v2, v2, v5
	ds_bpermute_b32 v4, v188, v0
	ds_bpermute_b32 v5, v188, v2
	s_waitcnt lgkmcnt(1)
	v_max_f32_e32 v4, v4, v4
	s_waitcnt lgkmcnt(0)
	v_max_f32_e32 v5, v5, v5
	v_max_f32_e32 v0, v0, v4
	v_max_f32_e32 v2, v2, v5
	ds_bpermute_b32 v4, v189, v0
	ds_bpermute_b32 v5, v189, v2
	s_waitcnt lgkmcnt(1)
	v_max_f32_e32 v4, v4, v4
	s_waitcnt lgkmcnt(0)
	v_max_f32_e32 v5, v5, v5
	v_max_f32_e32 v9, v0, v4
	v_max_f32_e32 v8, v2, v5
	ds_bpermute_b32 v11, v190, v9
	ds_bpermute_b32 v10, v190, v8
	s_waitcnt vmcnt(8) lgkmcnt(0)
	v_max_f32_e32 v0, v11, v11
	v_max_f32_e32 v2, v9, v9
	v_max_f32_e32 v0, v2, v0
	v_max_f32_e32 v2, v10, v10
	v_max_f32_e32 v4, v8, v8
	v_max_f32_e32 v2, v4, v2
	v_mul_f32_e32 v0, 0x4138aa3b, v0
	v_mul_f32_e32 v0, v2, v0
	v_mul_f32_e32 v177, 0x3fb8aa3b, v3
	v_max_f32_e32 v203, v0, v177
	s_waitcnt vmcnt(0) lgkmcnt(0)
	s_barrier
	v_xor_b32_e32 v18, 0x80000000, v203
	v_cndmask_b32_e64 v0, 0, 1, s[54:55]
	v_mov_b32_e32 v19, v18
	v_mov_b32_e32 v20, v18
	v_mov_b32_e32 v21, v18
	v_mov_b32_e32 v22, v18
	v_mov_b32_e32 v23, v18
	v_mov_b32_e32 v24, v18
	v_mov_b32_e32 v25, v18
	v_mov_b32_e32 v26, v18
	v_mov_b32_e32 v27, v18
	v_mov_b32_e32 v28, v18
	v_mov_b32_e32 v29, v18
	v_mov_b32_e32 v30, v18
	v_mov_b32_e32 v31, v18
	v_mov_b32_e32 v32, v18
	v_mov_b32_e32 v33, v18
	s_cmp_eq_u32 s43, 0
	v_cmp_ne_u32_e64 s[68:69], 1, v0
	s_cbranch_scc1 .LBB9_350
	s_mov_b64 s[56:57], s[72:73]
	s_mov_b64 s[72:73], s[88:89]
	v_readlane_b32 s88, v250, 9
	s_and_b64 vcc, exec, s[68:69]
	s_mov_b64 s[60:61], s[64:65]
	s_mov_b64 s[62:63], s[66:67]
	s_mov_b64 s[64:65], s[40:41]
	s_mov_b64 s[66:67], s[0:1]
	s_mov_b64 s[0:1], s[4:5]
	s_mov_b64 s[4:5], s[6:7]
	s_mov_b64 s[6:7], s[8:9]
	s_mov_b64 s[8:9], s[10:11]
	s_mov_b64 s[10:11], s[12:13]
	s_mov_b64 s[12:13], s[14:15]
	s_mov_b64 s[14:15], s[16:17]
	s_mov_b64 s[16:17], s[18:19]
	s_mov_b64 s[18:19], s[20:21]
	s_mov_b64 s[20:21], s[22:23]
	s_mov_b64 s[22:23], s[24:25]
	s_mov_b64 s[24:25], s[26:27]
	s_mov_b64 s[26:27], s[28:29]
	s_mov_b64 s[28:29], s[30:31]
	s_mov_b64 s[30:31], s[34:35]
	s_mov_b64 s[34:35], s[80:81]
	v_readlane_b32 s89, v250, 10
	v_readlane_b32 s90, v250, 11
	v_readlane_b32 s91, v250, 12
	v_readlane_b32 s92, v250, 13
	v_readlane_b32 s93, v250, 14
	v_readlane_b32 s94, v250, 15
	v_readlane_b32 s95, v250, 16
	s_cbranch_vccnz .LBB9_338
	s_lshl_b32 s48, s43, 16
	s_add_u32 s84, s96, s48
	s_addc_u32 s85, s97, 0
	s_lshl_b32 s47, s47, 1
	s_add_u32 s74, s51, s47
	s_addc_u32 s75, s46, 0
	v_mov_b32_e32 v3, v193
	v_mov_b32_e32 v2, v192
	s_mov_b32 s47, s50
	s_branch .LBB9_334
